# FoX phase: per-XCD dynamic unit queues (longest query block first) with stealing instead of static pairs; every unit through unit-1 code; next index prefetched under the prologue
# speedup vs baseline: 1.0293x; 1.0183x over previous
.Lq_init:
	s_add_u32 s90, s54, 0x80000
	s_addc_u32 s91, s55, 0
	s_getreg_b32 s92, hwreg(HW_REG_XCC_ID, 0, 4)
	s_and_b32 s92, s92, 7
.Lq_fetch:
	v_readfirstlane_b32 s96, v255
	s_cmp_lg_u32 s96, 0
	s_cbranch_scc1 .Lq_f1
	s_mov_b64 s[96:97], exec
.Lq_scan:
	s_mov_b64 exec, 0xff
	v_mbcnt_lo_u32_b32 v251, -1, 0
	v_lshlrev_b32_e32 v251, 6, v251
	global_load_dword v250, v251, s[90:91] sc1
	s_waitcnt vmcnt(0)
	v_cmp_gt_u32_e32 vcc, 0x80, v250
	s_mov_b32 s95, vcc_lo
	s_cmp_eq_u32 s95, 0
	s_cbranch_scc1 .Lq_none
	s_lshr_b32 s94, s95, s92
	s_lshl_b32 s94, s94, s92
	s_cmp_lg_u32 s94, 0
	s_cselect_b32 s95, s94, s95
	s_ff1_i32_b32 s92, s95
	s_mov_b64 exec, 1
	v_mov_b32_e32 v250, 1
	s_lshl_b32 s95, s92, 6
	v_mov_b32_e32 v251, s95
	global_atomic_add v250, v251, v250, s[90:91] sc0
	s_waitcnt vmcnt(0)
	v_readfirstlane_b32 s95, v250
	s_cmp_ge_u32 s95, 0x80
	s_cbranch_scc1 .Lq_scan
	s_lshl_b32 s94, s92, 8
	s_or_b32 s95, s95, s94
	s_branch .Lq_pub
.Lq_none:
	s_mov_b32 s95, 0x80000000
.Lq_pub:
	s_mov_b64 exec, 1
	v_mov_b32_e32 v251, s95
	v_mov_b32_e32 v252, 0x1c000
	ds_write_b32 v252, v251
	s_waitcnt lgkmcnt(0)
	s_mov_b64 exec, s[96:97]
.Lq_f1:
	s_barrier
.Lq_read:
	v_mov_b32_e32 v252, 0x1c000
	ds_read_b32 v250, v252
	s_waitcnt lgkmcnt(0)
	v_readfirstlane_b32 s95, v250
	s_barrier
	s_bitcmp1_b32 s95, 30
	s_cbranch_scc1 .Lq_fetch
	s_bitcmp1_b32 s95, 31
	s_cbranch_scc1 .LBB0_662
	s_lshr_b32 s92, s95, 8
	s_and_b32 s95, s95, 0xff
	s_lshr_b32 s94, s95, 3
	s_sub_i32 s94, 15, s94
	s_and_b32 s88, s95, 7
	s_lshl_b32 s96, s92, 3
	s_or_b32 s88, s88, s96
	s_lshl_b32 s88, s88, 3
.LBB0_626:
	v_readfirstlane_b32 s96, v255
	s_cmp_lg_u32 s96, 0
	s_cbranch_scc1 .Lq_p1
	s_mov_b64 s[96:97], exec
	s_mov_b64 exec, 1
	v_mov_b32_e32 v250, 1
	s_lshl_b32 s95, s92, 6
	v_mov_b32_e32 v251, s95
	global_atomic_add v250, v251, v250, s[90:91] sc0
	s_mov_b64 exec, s[96:97]
.Lq_p1:
	v_mov_b32_e32 v18, v255
	s_and_b32 s50, s88, 7
	s_ashr_i32 s0, s88, 7
	s_mov_b32 s51, s94
	v_readfirstlane_b32 s5, v18
	s_ashr_i32 s1, s0, 31
	s_ashr_i32 s33, s5, 1
	s_lshl_b64 s[22:23], s[0:1], 12
	s_lshl_b32 s60, s51, 8
	s_andn2_b32 s33, s33, 31
	s_bfe_u32 s4, s88, 0x40003
	s_lshl_b64 s[6:7], s[0:1], 26
	s_or_b32 s1, s22, s60
	s_ashr_i32 s16, s33, 31
	s_add_u32 s24, s1, s33
	v_and_b32_e32 v30, 31, v18
	s_addc_u32 s25, s23, s16
	v_or_b32_e32 v2, s24, v30
	v_mov_b32_e32 v3, s25
	v_lshlrev_b64 v[2:3], 14, v[2:3]
	v_bfe_u32 v31, v18, 5, 1
	v_lshl_add_u64 v[2:3], s[12:13], 0, v[2:3]
	s_lshl_b32 s16, s4, 8
	v_lshl_add_u64 v[2:3], v[2:3], 0, s[16:17]
	v_lshlrev_b32_e32 v0, 4, v31
	v_ashrrev_i32_e32 v19, 31, v18
	v_lshl_add_u64 v[2:3], v[2:3], 0, v[0:1]
	v_lshrrev_b32_e32 v0, 28, v19
	s_add_u32 s1, s12, s6
	v_add_u32_e32 v0, v18, v0
	s_addc_u32 s6, s13, s7
	v_ashrrev_i32_e32 v146, 4, v0
	v_and_b32_e32 v0, -16, v0
	s_add_u32 s20, s1, s16
	v_sub_u32_e32 v0, v18, v0
	v_ashrrev_i32_e32 v147, 31, v146
	global_load_dwordx4 v[98:101], v[2:3], off
	global_load_dwordx4 v[102:105], v[2:3], off offset:32
	global_load_dwordx4 v[106:109], v[2:3], off offset:64
	global_load_dwordx4 v[110:113], v[2:3], off offset:96
	global_load_dwordx4 v[114:117], v[2:3], off offset:128
	global_load_dwordx4 v[118:121], v[2:3], off offset:160
	global_load_dwordx4 v[122:125], v[2:3], off offset:192
	global_load_dwordx4 v[126:129], v[2:3], off offset:224
	s_addc_u32 s21, s6, 0
	v_lshlrev_b64 v[2:3], 14, v[146:147]
	v_lshlrev_b32_e32 v20, 3, v0
	s_lshl_b32 s84, s51, 22
	s_add_u32 s84, s84, 0x300000
	s_add_u32 s84, s20, s84
	s_addc_u32 s85, s21, 0
	s_sub_u32 s86, s84, 0x200000
	s_subb_u32 s87, s85, 0
	v_lshl_add_u64 v[2:3], s[84:85], 0, v[2:3]
	v_ashrrev_i32_e32 v21, 31, v20
	v_lshl_add_u64 v[2:3], v[20:21], 1, v[2:3]
	v_add_co_u32_e32 v2, vcc, s43, v2
	s_cmp_gt_u32 s5, 63
	s_nop 0
	v_addc_co_u32_e32 v3, vcc, 0, v3, vcc
	global_load_dwordx4 v[14:17], v[2:3], off offset:-4096
	global_load_dwordx4 v[10:13], v[2:3], off
	v_add_u32_e32 v2, 0x200, v18
	v_ashrrev_i32_e32 v3, 31, v2
	v_lshrrev_b32_e32 v3, 28, v3
	v_add_u32_e32 v3, v2, v3
	v_ashrrev_i32_e32 v148, 4, v3
	v_and_b32_e32 v3, -16, v3
	v_sub_u32_e32 v32, v2, v3
	v_ashrrev_i32_e32 v149, 31, v148
	v_lshlrev_b64 v[2:3], 14, v[148:149]
	v_lshlrev_b32_e32 v22, 3, v32
	v_lshl_add_u64 v[2:3], s[84:85], 0, v[2:3]
	v_ashrrev_i32_e32 v23, 31, v22
	v_lshl_add_u64 v[2:3], v[22:23], 1, v[2:3]
	v_add_co_u32_e32 v4, vcc, 0x1000, v2
	v_and_b32_e32 v156, 63, v18
	s_nop 0
	v_addc_co_u32_e32 v5, vcc, 0, v3, vcc
	v_add_co_u32_e32 v6, vcc, 0x2000, v2
	s_nop 1
	v_addc_co_u32_e32 v7, vcc, 0, v3, vcc
	global_load_dwordx4 v[2:5], v[4:5], off
	s_nop 0
	global_load_dwordx4 v[6:9], v[6:7], off
	s_cbranch_scc1 .LBB0_628
	s_lshl_b32 s1, s0, 10
	v_lshl_or_b32 v24, v156, 4, s1
	v_or_b32_e32 v24, s4, v24
	v_ashrrev_i32_e32 v25, 31, v24
	v_lshl_add_u64 v[24:25], v[24:25], 2, s[14:15]
	global_load_dword v24, v[24:25], off
	v_and_b32_e32 v25, 64, v154
	v_add_u32_e32 v26, -1, v154
	v_cmp_lt_i32_e32 vcc, v26, v25
	v_add_u32_e32 v27, -2, v154
	v_add_u32_e32 v28, -4, v154
	v_cndmask_b32_e32 v26, v26, v154, vcc
	v_lshlrev_b32_e32 v26, 2, v26
	v_cmp_lt_i32_e32 vcc, v27, v25
	s_waitcnt vmcnt(0)
	ds_bpermute_b32 v26, v26, v24
	v_cndmask_b32_e32 v27, v27, v154, vcc
	v_cmp_eq_u32_e32 vcc, 0, v156
	v_lshlrev_b32_e32 v27, 2, v27
	s_waitcnt lgkmcnt(0)
	v_add_f32_e32 v26, v24, v26
	v_cndmask_b32_e32 v26, v26, v24, vcc
	ds_bpermute_b32 v27, v27, v26
	v_cmp_lt_i32_e32 vcc, v28, v25
	s_waitcnt lgkmcnt(0)
	v_add_f32_e32 v27, v26, v27
	v_cndmask_b32_e32 v28, v28, v154, vcc
	v_cmp_gt_u32_e32 vcc, 2, v156
	v_lshlrev_b32_e32 v28, 2, v28
	s_nop 0
	v_cndmask_b32_e32 v26, v27, v26, vcc
	ds_bpermute_b32 v27, v28, v26
	v_add_u32_e32 v28, -8, v154
	v_cmp_lt_i32_e32 vcc, v28, v25
	s_waitcnt lgkmcnt(0)
	v_add_f32_e32 v27, v26, v27
	v_cndmask_b32_e32 v28, v28, v154, vcc
	v_cmp_gt_u32_e32 vcc, 4, v156
	v_lshlrev_b32_e32 v28, 2, v28
	s_nop 0
	v_cndmask_b32_e32 v26, v27, v26, vcc
	ds_bpermute_b32 v27, v28, v26
	v_add_u32_e32 v28, -16, v154
	v_cmp_lt_i32_e32 vcc, v28, v25
	s_waitcnt lgkmcnt(0)
	v_add_f32_e32 v27, v26, v27
	v_cndmask_b32_e32 v28, v28, v154, vcc
	v_cmp_gt_u32_e32 vcc, 8, v156
	v_lshlrev_b32_e32 v28, 2, v28
	s_nop 0
	v_cndmask_b32_e32 v26, v27, v26, vcc
	ds_bpermute_b32 v27, v28, v26
	v_subrev_u32_e32 v28, 32, v154
	v_cmp_lt_i32_e32 vcc, v28, v25
	s_waitcnt lgkmcnt(0)
	v_add_f32_e32 v27, v26, v27
	v_cndmask_b32_e32 v25, v28, v154, vcc
	v_cmp_gt_u32_e32 vcc, 16, v156
	v_lshlrev_b32_e32 v25, 2, v25
	s_nop 0
	v_cndmask_b32_e32 v26, v27, v26, vcc
	ds_bpermute_b32 v25, v25, v26
	v_cmp_gt_u32_e32 vcc, 32, v156
	v_lshl_add_u32 v27, v156, 2, 0
	s_waitcnt lgkmcnt(0)
	v_add_f32_e32 v25, v26, v25
	v_cndmask_b32_e32 v25, v25, v26, vcc
	v_sub_f32_e32 v24, v25, v24
	v_add_u32_e32 v25, 0x16800, v27
	ds_write_b32 v25, v24

.LBB0_646:
	v_mul_lo_u32 v157, v146, s45
	v_lshlrev_b32_e32 v158, 4, v0
	v_add3_u32 v0, 0, v157, v158
	s_waitcnt vmcnt(0)
	v_readfirstlane_b32 s96, v255
	s_cmp_lg_u32 s96, 0
	s_cbranch_scc1 .Lq_w1
	s_mov_b64 s[96:97], exec
	s_mov_b64 exec, 1
	s_lshl_b32 s95, s92, 8
	v_or_b32_e32 v251, s95, v250
	v_mov_b32_e32 v253, 0x40000000
	v_cmp_gt_u32_e32 vcc, 0x80, v250
	v_mov_b32_e32 v252, 0x1c000
	v_cndmask_b32_e32 v251, v253, v251, vcc
	ds_write_b32 v252, v251
	s_mov_b64 exec, s[96:97]
.Lq_w1:
	ds_write_b128 v0, v[14:17]
	v_mad_u64_u32 v[14:15], s[4:5], v146, 48, v[0:1]
	ds_write_b128 v14, v[10:13] offset:34816
	v_lshlrev_b64 v[10:11], 14, v[146:147]
	v_lshl_add_u64 v[10:11], s[86:87], 0, v[10:11]
	v_lshlrev_b64 v[12:13], 1, v[20:21]
	v_lshl_add_u64 v[10:11], v[10:11], 0, v[12:13]
	v_add_co_u32_e32 v10, vcc, s47, v10
	v_lshlrev_b64 v[14:15], 1, v[22:23]
	s_nop 0
	v_addc_co_u32_e32 v11, vcc, 0, v11, vcc
	global_load_dwordx4 v[130:133], v[10:11], off offset:-4096
	global_load_dwordx4 v[134:137], v[10:11], off
	v_lshlrev_b64 v[10:11], 14, v[148:149]
	v_lshl_add_u64 v[10:11], s[86:87], 0, v[10:11]
	v_lshl_add_u64 v[10:11], v[10:11], 0, v[14:15]
	v_add_co_u32_e32 v10, vcc, s47, v10
	v_mul_lo_u32 v160, v148, s45
	s_nop 0
	v_addc_co_u32_e32 v11, vcc, 0, v11, vcc
	global_load_dwordx4 v[138:141], v[10:11], off offset:-4096
	global_load_dwordx4 v[142:145], v[10:11], off
	v_lshlrev_b32_e32 v161, 4, v32
	v_add3_u32 v0, 0, v160, v161
	ds_write_b128 v0, v[2:5]
	v_mad_u64_u32 v[2:3], s[4:5], v148, 48, v[0:1]
	v_lshrrev_b32_e32 v0, 2, v18
	v_lshlrev_b32_e32 v163, 2, v31
	ds_write_b128 v2, v[6:9] offset:34816
	v_and_or_b32 v0, v0, 3, v163
	v_lshlrev_b32_e32 v2, 1, v18
	v_lshlrev_b32_e32 v3, 3, v18
	s_add_i32 s5, s33, s60
	v_lshl_add_u32 v149, v31, 4, 0
	v_mad_u32_u24 v0, v0, s46, 0
	v_and_b32_e32 v2, 32, v2
	v_and_b32_e32 v3, 24, v3
	v_lshl_add_u32 v152, v148, 14, v14
	v_mov_b32_e32 v14, v1
	v_mov_b32_e32 v15, v1
	v_mad_u32_u24 v162, v30, s45, v149
	v_add3_u32 v164, v0, v2, v3
	v_lshl_add_u32 v150, v146, 14, v12
	s_mov_b64 s[78:79], s[20:21]
	v_add_u32_e32 v195, s5, v30
	v_mov_b32_e32 v0, v1
	v_mov_b32_e32 v2, v1
	v_mov_b32_e32 v3, v1
	v_mov_b32_e32 v4, v1
	v_mov_b32_e32 v5, v1
	v_mov_b32_e32 v6, v1
	v_mov_b32_e32 v7, v1
	v_mov_b32_e32 v8, v1
	v_mov_b32_e32 v9, v1
	v_mov_b32_e32 v10, v1
	v_mov_b32_e32 v11, v1
	v_mov_b32_e32 v12, v1
	v_mov_b32_e32 v13, v1
	v_mov_b64_e32 v[64:65], v[14:15]
	v_mov_b64_e32 v[48:49], v[14:15]
	v_mov_b64_e32 v[32:33], v[14:15]
	s_lshl_b32 s6, s51, 2
	s_lshl_b32 s7, s51, 10
	v_mov_b64_e32 v[62:63], v[12:13]
	v_mov_b64_e32 v[60:61], v[10:11]
	v_mov_b64_e32 v[58:59], v[8:9]
	v_mov_b64_e32 v[56:57], v[6:7]
	v_mov_b64_e32 v[54:55], v[4:5]
	v_mov_b64_e32 v[52:53], v[2:3]
	v_mov_b64_e32 v[50:51], v[0:1]
	v_mov_b64_e32 v[46:47], v[12:13]
	v_mov_b64_e32 v[44:45], v[10:11]
	v_mov_b64_e32 v[42:43], v[8:9]
	v_mov_b64_e32 v[40:41], v[6:7]
	v_mov_b64_e32 v[38:39], v[4:5]
	v_mov_b64_e32 v[36:37], v[2:3]
	v_mov_b64_e32 v[34:35], v[0:1]
	v_mov_b64_e32 v[30:31], v[12:13]
	v_mov_b64_e32 v[28:29], v[10:11]
	v_mov_b64_e32 v[26:27], v[8:9]
	v_mov_b64_e32 v[24:25], v[6:7]
	v_mov_b64_e32 v[22:23], v[4:5]
	v_mov_b64_e32 v[20:21], v[2:3]
	v_mov_b64_e32 v[18:19], v[0:1]
	v_mov_b64_e32 v[16:17], v[14:15]
	s_mov_b32 s0, 2
	s_add_i32 s1, s6, 4
	v_mul_lo_u32 v159, v146, s46
	v_mul_lo_u32 v147, v148, s46
	s_mov_b32 s4, 0
	s_or_b32 s6, s6, 3
	v_or_b32_e32 v165, 32, v163
	v_or_b32_e32 v166, 33, v163
	v_or_b32_e32 v167, 2, v163
	v_or_b32_e32 v168, 34, v163
	v_or_b32_e32 v169, 3, v163
	v_or_b32_e32 v170, 35, v163
	v_or_b32_e32 v171, 8, v163
	v_or_b32_e32 v172, 40, v163
	v_or_b32_e32 v173, 9, v163
	v_or_b32_e32 v174, 41, v163
	v_or_b32_e32 v175, 10, v163
	v_or_b32_e32 v176, 42, v163
	v_or_b32_e32 v177, 11, v163
	v_or_b32_e32 v178, 43, v163
	v_or_b32_e32 v179, 16, v163
	v_or_b32_e32 v180, 48, v163
	v_or_b32_e32 v181, 17, v163
	v_or_b32_e32 v182, 49, v163
	v_or_b32_e32 v183, 18, v163
	v_or_b32_e32 v184, 50, v163
	v_or_b32_e32 v185, 19, v163
	v_or_b32_e32 v186, 51, v163
	v_or_b32_e32 v187, 24, v163
	v_or_b32_e32 v188, 56, v163
	v_or_b32_e32 v189, 25, v163
	v_or_b32_e32 v190, 57, v163
	v_or_b32_e32 v191, 26, v163
	v_or_b32_e32 v192, 58, v163
	v_or_b32_e32 v193, 27, v163
	v_or_b32_e32 v194, 59, v163
	s_addk_i32 s7, 0x400
	v_mov_b32_e32 v196, 0
	v_mov_b32_e32 v197, 0xf149f2ca
	s_mov_b32 s26, 63
	v_mov_b64_e32 v[14:15], v[12:13]
	v_mov_b64_e32 v[12:13], v[10:11]
	v_mov_b64_e32 v[10:11], v[8:9]
	v_mov_b64_e32 v[8:9], v[6:7]
	v_mov_b64_e32 v[6:7], v[4:5]
	v_mov_b64_e32 v[4:5], v[2:3]
	v_mov_b64_e32 v[2:3], v[0:1]
	s_waitcnt lgkmcnt(0)
	s_movk_i32 s68, 0x5000
	s_mov_b32 s69, 0
	s_mov_b32 s70, 0xe800
	s_mov_b32 s72, 0
	s_lshl_b32 s77, s6, 6
	v_subrev_u32_e32 v195, s77, v195
	s_barrier
	v_readfirstlane_b32 s73, v255
	s_cmp_lt_u32 s73, 0x100
	s_cbranch_scc1 .Lyp649
	s_setprio 1

.LBB0_654:
	s_setprio 0
	v_mov_b32_e32 v0, v196
	v_nop
	v_nop
	v_permlane32_swap_b32 v196, v0
	s_lshl_b32 s16, s16, 1
	v_add_f32_e32 v146, v196, v0
	v_ashrrev_i32_e32 v0, 31, v156
	v_lshrrev_b32_e32 v0, 28, v0
	v_add_u32_e32 v0, v156, v0
	s_waitcnt vmcnt(0)
	v_ashrrev_i32_e32 v144, 4, v0
	v_and_b32_e32 v0, -16, v0
	v_sub_u32_e32 v147, v156, v0
	v_lshlrev_b32_e32 v68, 3, v147
	v_ashrrev_i32_e32 v69, 31, v68
	v_add_u32_e32 v0, 64, v156
	v_lshlrev_b64 v[140:141], 1, v[68:69]
	v_ashrrev_i32_e32 v68, 31, v0
	v_lshrrev_b32_e32 v68, 28, v68
	v_ashrrev_i32_e32 v145, 31, v144
	v_add_u32_e32 v68, v0, v68
	v_lshl_add_u64 v[138:139], s[24:25], 0, v[144:145]
	v_ashrrev_i32_e32 v142, 4, v68
	v_lshlrev_b64 v[66:67], 14, v[138:139]
	v_and_b32_e32 v68, -16, v68
	v_ashrrev_i32_e32 v143, 31, v142
	v_lshl_add_u64 v[66:67], s[12:13], 0, v[66:67]
	v_sub_u32_e32 v145, v0, v68
	v_lshl_add_u64 v[132:133], s[24:25], 0, v[142:143]
	v_lshl_add_u64 v[66:67], v[66:67], 0, s[16:17]
	v_lshlrev_b64 v[68:69], 14, v[132:133]
	v_lshlrev_b32_e32 v70, 3, v145
	v_lshl_add_u64 v[66:67], v[66:67], 0, v[140:141]
	v_lshl_add_u64 v[68:69], s[12:13], 0, v[68:69]
	v_ashrrev_i32_e32 v71, 31, v70
	v_add_co_u32_e32 v66, vcc, s48, v66
	v_lshl_add_u64 v[68:69], v[68:69], 0, s[16:17]
	v_lshlrev_b64 v[134:135], 1, v[70:71]
	v_addc_co_u32_e32 v67, vcc, 0, v67, vcc
	v_lshl_add_u64 v[68:69], v[68:69], 0, v[134:135]
	v_add_co_u32_e32 v68, vcc, s48, v68
	v_add_u32_e32 v0, 0x80, v156
	s_nop 0
	v_addc_co_u32_e32 v69, vcc, 0, v69, vcc
	global_load_dwordx4 v[94:97], v[66:67], off
	global_load_dwordx4 v[90:93], v[68:69], off
	v_ashrrev_i32_e32 v66, 31, v0
	v_lshrrev_b32_e32 v66, 28, v66
	v_add_u32_e32 v66, v0, v66
	v_ashrrev_i32_e32 v136, 4, v66
	v_and_b32_e32 v66, -16, v66
	v_sub_u32_e32 v143, v0, v66
	v_lshlrev_b32_e32 v68, 3, v143
	v_ashrrev_i32_e32 v69, 31, v68
	v_add_u32_e32 v0, 0xc0, v156
	v_lshlrev_b64 v[128:129], 1, v[68:69]
	v_ashrrev_i32_e32 v68, 31, v0
	v_lshrrev_b32_e32 v68, 28, v68
	v_ashrrev_i32_e32 v137, 31, v136
	v_add_u32_e32 v68, v0, v68
	v_lshl_add_u64 v[126:127], s[24:25], 0, v[136:137]
	v_ashrrev_i32_e32 v130, 4, v68
	v_lshlrev_b64 v[66:67], 14, v[126:127]
	v_and_b32_e32 v68, -16, v68
	v_ashrrev_i32_e32 v131, 31, v130
	v_lshl_add_u64 v[66:67], s[12:13], 0, v[66:67]
	v_sub_u32_e32 v137, v0, v68
	v_lshl_add_u64 v[120:121], s[24:25], 0, v[130:131]
	v_lshl_add_u64 v[66:67], v[66:67], 0, s[16:17]
	v_lshlrev_b64 v[68:69], 14, v[120:121]
	v_lshlrev_b32_e32 v70, 3, v137
	v_lshl_add_u64 v[66:67], v[66:67], 0, v[128:129]
	v_lshl_add_u64 v[68:69], s[12:13], 0, v[68:69]
	v_ashrrev_i32_e32 v71, 31, v70
	v_add_co_u32_e32 v66, vcc, s48, v66
	v_lshl_add_u64 v[68:69], v[68:69], 0, s[16:17]
	v_lshlrev_b64 v[122:123], 1, v[70:71]
	v_addc_co_u32_e32 v67, vcc, 0, v67, vcc
	v_lshl_add_u64 v[68:69], v[68:69], 0, v[122:123]
	v_add_co_u32_e32 v68, vcc, s48, v68
	v_add_u32_e32 v0, 0x100, v156
	s_nop 0
	v_addc_co_u32_e32 v69, vcc, 0, v69, vcc
	global_load_dwordx4 v[86:89], v[66:67], off
	global_load_dwordx4 v[82:85], v[68:69], off
	v_ashrrev_i32_e32 v66, 31, v0
	v_lshrrev_b32_e32 v66, 28, v66
	v_add_u32_e32 v66, v0, v66
	v_ashrrev_i32_e32 v124, 4, v66
	v_and_b32_e32 v66, -16, v66
	v_sub_u32_e32 v131, v0, v66
	v_lshlrev_b32_e32 v68, 3, v131
	v_ashrrev_i32_e32 v69, 31, v68
	v_add_u32_e32 v0, 0x140, v156
	v_lshlrev_b64 v[116:117], 1, v[68:69]
	v_ashrrev_i32_e32 v68, 31, v0
	v_lshrrev_b32_e32 v68, 28, v68
	v_ashrrev_i32_e32 v125, 31, v124
	v_add_u32_e32 v68, v0, v68
	v_lshl_add_u64 v[114:115], s[24:25], 0, v[124:125]
	v_ashrrev_i32_e32 v118, 4, v68
	v_lshlrev_b64 v[66:67], 14, v[114:115]
	v_and_b32_e32 v68, -16, v68
	v_ashrrev_i32_e32 v119, 31, v118
	v_lshl_add_u64 v[66:67], s[12:13], 0, v[66:67]
	v_sub_u32_e32 v125, v0, v68
	v_lshl_add_u64 v[108:109], s[24:25], 0, v[118:119]
	v_lshl_add_u64 v[66:67], v[66:67], 0, s[16:17]
	v_lshlrev_b64 v[68:69], 14, v[108:109]
	v_lshlrev_b32_e32 v70, 3, v125
	v_lshl_add_u64 v[66:67], v[66:67], 0, v[116:117]
	v_lshl_add_u64 v[68:69], s[12:13], 0, v[68:69]
	v_ashrrev_i32_e32 v71, 31, v70
	v_add_co_u32_e32 v66, vcc, s48, v66
	v_lshl_add_u64 v[68:69], v[68:69], 0, s[16:17]
	v_lshlrev_b64 v[110:111], 1, v[70:71]
	v_addc_co_u32_e32 v67, vcc, 0, v67, vcc
	v_lshl_add_u64 v[68:69], v[68:69], 0, v[110:111]
	v_add_co_u32_e32 v68, vcc, s48, v68
	v_add_u32_e32 v0, 0x180, v156
	s_nop 0
	v_addc_co_u32_e32 v69, vcc, 0, v69, vcc
	global_load_dwordx4 v[78:81], v[66:67], off
	global_load_dwordx4 v[74:77], v[68:69], off
	v_ashrrev_i32_e32 v66, 31, v0
	v_lshrrev_b32_e32 v66, 28, v66
	v_add_u32_e32 v66, v0, v66
	v_ashrrev_i32_e32 v112, 4, v66
	v_and_b32_e32 v66, -16, v66
	v_sub_u32_e32 v119, v0, v66
	v_lshlrev_b32_e32 v68, 3, v119
	v_ashrrev_i32_e32 v69, 31, v68
	v_add_u32_e32 v0, 0x1c0, v156
	v_lshlrev_b64 v[104:105], 1, v[68:69]
	v_ashrrev_i32_e32 v68, 31, v0
	v_lshrrev_b32_e32 v68, 28, v68
	v_ashrrev_i32_e32 v113, 31, v112
	v_add_u32_e32 v68, v0, v68
	v_lshl_add_u64 v[102:103], s[24:25], 0, v[112:113]
	v_ashrrev_i32_e32 v106, 4, v68
	v_lshlrev_b64 v[66:67], 14, v[102:103]
	v_and_b32_e32 v68, -16, v68
	v_ashrrev_i32_e32 v107, 31, v106
	s_and_b32 s0, s49, 7
	v_lshl_add_u64 v[66:67], s[12:13], 0, v[66:67]
	v_sub_u32_e32 v0, v0, v68
	v_lshl_add_u64 v[98:99], s[24:25], 0, v[106:107]
	s_lshl_b32 s7, s0, 8
	s_lshl_b32 s6, s0, 10
	v_lshl_add_u64 v[66:67], v[66:67], 0, s[16:17]
	v_lshlrev_b64 v[68:69], 14, v[98:99]
	v_lshlrev_b32_e32 v70, 3, v0
	v_div_scale_f32 v107, s[0:1], v146, v146, 1.0
	v_lshl_add_u64 v[66:67], v[66:67], 0, v[104:105]
	v_lshl_add_u64 v[68:69], s[12:13], 0, v[68:69]
	v_ashrrev_i32_e32 v71, 31, v70
	v_rcp_f32_e32 v113, v107
	v_add_co_u32_e32 v66, vcc, s48, v66
	v_lshl_add_u64 v[68:69], v[68:69], 0, s[16:17]
	v_lshlrev_b64 v[100:101], 1, v[70:71]
	v_addc_co_u32_e32 v67, vcc, 0, v67, vcc
	v_lshl_add_u64 v[68:69], v[68:69], 0, v[100:101]
	v_add_co_u32_e32 v68, vcc, s48, v68
	v_fma_f32 v148, -v107, v113, 1.0
	s_nop 0
	v_addc_co_u32_e32 v69, vcc, 0, v69, vcc
	v_fmac_f32_e32 v113, v148, v113
	v_div_scale_f32 v148, vcc, 1.0, v146, 1.0
	v_mul_f32_e32 v149, v148, v113
	v_fma_f32 v150, -v107, v149, v148
	v_fmac_f32_e32 v149, v150, v113
	v_fma_f32 v107, -v107, v149, v148
	v_div_fmas_f32 v107, v107, v113, v149
	v_div_fixup_f32 v146, v107, v146, 1.0
	v_pk_mul_f32 v[50:51], v[50:51], v[146:147] op_sel_hi:[1,0]
	v_pk_mul_f32 v[52:53], v[52:53], v[146:147] op_sel_hi:[1,0]
	s_mulk_i32 s33, 0x110
	v_and_b32_e32 v107, 31, v156
	v_cvt_pk_bf16_f32 v50, v50, v51
	v_cvt_pk_bf16_f32 v51, v52, v53
	v_ashrrev_i32_e32 v52, 2, v156
	v_pk_mul_f32 v[2:3], v[2:3], v[146:147] op_sel_hi:[1,0]
	v_pk_mul_f32 v[4:5], v[4:5], v[146:147] op_sel_hi:[1,0]
	s_add_i32 s4, s33, 0
	v_mul_u32_u24_e32 v107, 0x110, v107
	v_and_b32_e32 v52, -8, v52
	v_cvt_pk_bf16_f32 v2, v2, v3
	v_cvt_pk_bf16_f32 v3, v4, v5
	v_pk_mul_f32 v[4:5], v[6:7], v[146:147] op_sel_hi:[1,0]
	v_pk_mul_f32 v[6:7], v[8:9], v[146:147] op_sel_hi:[1,0]
	v_add3_u32 v107, s4, v107, v52
	v_cvt_pk_bf16_f32 v4, v4, v5
	v_cvt_pk_bf16_f32 v5, v6, v7
	global_load_dwordx4 v[70:73], v[66:67], off
	s_nop 0
	global_load_dwordx4 v[66:69], v[68:69], off
	v_pk_mul_f32 v[34:35], v[34:35], v[146:147] op_sel_hi:[1,0]
	v_pk_mul_f32 v[36:37], v[36:37], v[146:147] op_sel_hi:[1,0]
	v_pk_mul_f32 v[18:19], v[18:19], v[146:147] op_sel_hi:[1,0]
	v_pk_mul_f32 v[20:21], v[20:21], v[146:147] op_sel_hi:[1,0]
	ds_write2_b64 v107, v[2:3], v[4:5] offset0:24 offset1:26
	v_pk_mul_f32 v[2:3], v[10:11], v[146:147] op_sel_hi:[1,0]
	v_pk_mul_f32 v[4:5], v[12:13], v[146:147] op_sel_hi:[1,0]
	v_pk_mul_f32 v[52:53], v[54:55], v[146:147] op_sel_hi:[1,0]
	v_pk_mul_f32 v[54:55], v[56:57], v[146:147] op_sel_hi:[1,0]
	v_cvt_pk_bf16_f32 v34, v34, v35
	v_cvt_pk_bf16_f32 v35, v36, v37
	v_pk_mul_f32 v[36:37], v[38:39], v[146:147] op_sel_hi:[1,0]
	v_pk_mul_f32 v[38:39], v[40:41], v[146:147] op_sel_hi:[1,0]
	v_cvt_pk_bf16_f32 v18, v18, v19
	v_cvt_pk_bf16_f32 v19, v20, v21
	v_pk_mul_f32 v[20:21], v[22:23], v[146:147] op_sel_hi:[1,0]
	v_pk_mul_f32 v[22:23], v[24:25], v[146:147] op_sel_hi:[1,0]
	v_cvt_pk_bf16_f32 v2, v2, v3
	v_cvt_pk_bf16_f32 v3, v4, v5
	v_pk_mul_f32 v[4:5], v[14:15], v[146:147] op_sel_hi:[1,0]
	v_pk_mul_f32 v[6:7], v[16:17], v[146:147] op_sel_hi:[1,0]
	v_cvt_pk_bf16_f32 v52, v52, v53
	v_cvt_pk_bf16_f32 v53, v54, v55
	v_cvt_pk_bf16_f32 v36, v36, v37
	v_cvt_pk_bf16_f32 v37, v38, v39
	v_cvt_pk_bf16_f32 v20, v20, v21
	v_cvt_pk_bf16_f32 v21, v22, v23
	v_cvt_pk_bf16_f32 v4, v4, v5
	v_cvt_pk_bf16_f32 v5, v6, v7
	ds_write2_b64 v107, v[50:51], v[52:53] offset1:2
	v_pk_mul_f32 v[50:51], v[58:59], v[146:147] op_sel_hi:[1,0]
	v_pk_mul_f32 v[52:53], v[60:61], v[146:147] op_sel_hi:[1,0]
	ds_write2_b64 v107, v[34:35], v[36:37] offset0:8 offset1:10
	v_pk_mul_f32 v[34:35], v[42:43], v[146:147] op_sel_hi:[1,0]
	v_pk_mul_f32 v[36:37], v[44:45], v[146:147] op_sel_hi:[1,0]
	ds_write2_b64 v107, v[18:19], v[20:21] offset0:16 offset1:18
	v_pk_mul_f32 v[18:19], v[26:27], v[146:147] op_sel_hi:[1,0]
	v_pk_mul_f32 v[20:21], v[28:29], v[146:147] op_sel_hi:[1,0]
	ds_write2_b64 v107, v[2:3], v[4:5] offset0:28 offset1:30
	v_mul_lo_u32 v2, v144, s45
	v_lshlrev_b32_e32 v3, 4, v147
	s_waitcnt vmcnt(7)
	v_lshlrev_b32_e32 v10, 16, v94
	v_cvt_pk_bf16_f32 v50, v50, v51
	v_cvt_pk_bf16_f32 v51, v52, v53
	v_pk_mul_f32 v[52:53], v[62:63], v[146:147] op_sel_hi:[1,0]
	v_pk_mul_f32 v[54:55], v[64:65], v[146:147] op_sel_hi:[1,0]
	v_cvt_pk_bf16_f32 v34, v34, v35
	v_cvt_pk_bf16_f32 v35, v36, v37
	v_pk_mul_f32 v[36:37], v[46:47], v[146:147] op_sel_hi:[1,0]
	v_pk_mul_f32 v[38:39], v[48:49], v[146:147] op_sel_hi:[1,0]
	v_cvt_pk_bf16_f32 v18, v18, v19
	v_cvt_pk_bf16_f32 v19, v20, v21
	v_pk_mul_f32 v[20:21], v[30:31], v[146:147] op_sel_hi:[1,0]
	v_pk_mul_f32 v[22:23], v[32:33], v[146:147] op_sel_hi:[1,0]
	v_add3_u32 v2, s4, v2, v3
	v_and_b32_e32 v13, 0xffff0000, v94
	v_mul_f32_e32 v3, 0xbfb8aa3b, v10
	v_cvt_pk_bf16_f32 v52, v52, v53
	v_cvt_pk_bf16_f32 v53, v54, v55
	v_cvt_pk_bf16_f32 v36, v36, v37
	v_cvt_pk_bf16_f32 v37, v38, v39
	v_cvt_pk_bf16_f32 v20, v20, v21
	v_cvt_pk_bf16_f32 v21, v22, v23
	v_exp_f32_e32 v6, v3
	v_mul_f32_e32 v3, 0xbfb8aa3b, v13
	ds_write2_b64 v107, v[50:51], v[52:53] offset0:4 offset1:6
	ds_write2_b64 v107, v[34:35], v[36:37] offset0:12 offset1:14
	ds_write2_b64 v107, v[18:19], v[20:21] offset0:20 offset1:22
	v_exp_f32_e32 v7, v3
	s_waitcnt lgkmcnt(0)
	ds_read_b128 v[2:5], v2
	v_add_f32_e32 v6, 1.0, v6
	v_rcp_f32_e32 v14, v6
	v_add_f32_e32 v6, 1.0, v7
	v_rcp_f32_e32 v15, v6
	v_mul_lo_u32 v6, v142, s45
	v_lshlrev_b32_e32 v7, 4, v145
	v_add3_u32 v6, s4, v6, v7
	ds_read_b128 v[6:9], v6
	s_waitcnt lgkmcnt(1)
	v_and_b32_e32 v11, 0xffff0000, v2
	v_lshlrev_b32_e32 v12, 16, v2
	v_pk_mul_f32 v[10:11], v[12:13], v[10:11]
	v_lshlrev_b32_e32 v12, 16, v95
	v_pk_mul_f32 v[10:11], v[14:15], v[10:11]
	v_and_b32_e32 v15, 0xffff0000, v95
	v_mul_f32_e32 v2, 0xbfb8aa3b, v12
	v_exp_f32_e32 v13, v2
	v_mul_f32_e32 v2, 0xbfb8aa3b, v15
	v_exp_f32_e32 v14, v2
	v_cvt_pk_bf16_f32 v2, v10, v11
	v_add_f32_e32 v10, 1.0, v13
	v_rcp_f32_e32 v10, v10
	v_add_f32_e32 v11, 1.0, v14
	v_rcp_f32_e32 v11, v11
	v_and_b32_e32 v13, 0xffff0000, v3
	v_lshlrev_b32_e32 v14, 16, v3
	v_pk_mul_f32 v[12:13], v[14:15], v[12:13]
	v_and_b32_e32 v15, 0xffff0000, v96
	v_pk_mul_f32 v[10:11], v[10:11], v[12:13]
	v_lshlrev_b32_e32 v12, 16, v96
	v_mul_f32_e32 v3, 0xbfb8aa3b, v12
	v_exp_f32_e32 v13, v3
	v_mul_f32_e32 v3, 0xbfb8aa3b, v15
	v_exp_f32_e32 v14, v3
	v_cvt_pk_bf16_f32 v3, v10, v11
	v_add_f32_e32 v10, 1.0, v13
	v_rcp_f32_e32 v10, v10
	v_add_f32_e32 v11, 1.0, v14
	v_rcp_f32_e32 v11, v11
	v_and_b32_e32 v13, 0xffff0000, v4
	v_lshlrev_b32_e32 v14, 16, v4
	v_pk_mul_f32 v[12:13], v[14:15], v[12:13]
	v_and_b32_e32 v15, 0xffff0000, v97
	v_pk_mul_f32 v[10:11], v[10:11], v[12:13]
	v_lshlrev_b32_e32 v12, 16, v97
	v_mul_f32_e32 v4, 0xbfb8aa3b, v12
	v_exp_f32_e32 v13, v4
	v_mul_f32_e32 v4, 0xbfb8aa3b, v15
	v_exp_f32_e32 v14, v4
	v_cvt_pk_bf16_f32 v4, v10, v11
	v_add_f32_e32 v10, 1.0, v13
	v_rcp_f32_e32 v10, v10
	v_add_f32_e32 v11, 1.0, v14
	v_rcp_f32_e32 v11, v11
	v_and_b32_e32 v13, 0xffff0000, v5
	v_lshlrev_b32_e32 v14, 16, v5
	v_pk_mul_f32 v[12:13], v[14:15], v[12:13]
	s_waitcnt vmcnt(6)
	v_and_b32_e32 v15, 0xffff0000, v90
	v_pk_mul_f32 v[10:11], v[10:11], v[12:13]
	v_lshlrev_b32_e32 v12, 16, v90
	s_addk_i32 s6, 0x400
	v_mul_f32_e32 v13, 0xbfb8aa3b, v12
	v_mul_f32_e32 v14, 0xbfb8aa3b, v15
	s_add_u32 s0, s36, s16
	v_exp_f32_e32 v13, v13
	v_exp_f32_e32 v14, v14
	s_addc_u32 s1, s37, 0
	v_cvt_pk_bf16_f32 v5, v10, v11
	v_lshlrev_b64 v[10:11], 12, v[138:139]
	v_lshl_add_u64 v[10:11], s[0:1], 0, v[10:11]
	v_lshl_add_u64 v[10:11], v[10:11], 0, v[140:141]
	global_store_dwordx4 v[10:11], v[2:5], off
	v_and_b32_e32 v11, 0xffff0000, v91
	s_waitcnt lgkmcnt(0)
	v_lshlrev_b32_e32 v10, 16, v7
	v_add_f32_e32 v2, 1.0, v13
	v_add_f32_e32 v3, 1.0, v14
	v_rcp_f32_e32 v2, v2
	v_rcp_f32_e32 v3, v3
	v_and_b32_e32 v13, 0xffff0000, v6
	v_lshlrev_b32_e32 v14, 16, v6
	v_pk_mul_f32 v[4:5], v[14:15], v[12:13]
	v_mul_f32_e32 v6, 0xbfb8aa3b, v11
	v_pk_mul_f32 v[2:3], v[2:3], v[4:5]
	v_lshlrev_b32_e32 v4, 16, v91
	v_mul_f32_e32 v5, 0xbfb8aa3b, v4
	v_exp_f32_e32 v5, v5
	v_exp_f32_e32 v6, v6
	v_cvt_pk_bf16_f32 v2, v2, v3
	v_lshlrev_b32_e32 v0, 4, v0
	v_add_f32_e32 v3, 1.0, v5
	v_rcp_f32_e32 v12, v3
	v_add_f32_e32 v3, 1.0, v6
	v_and_b32_e32 v5, 0xffff0000, v7
	v_lshlrev_b32_e32 v6, 16, v92
	v_rcp_f32_e32 v13, v3
	v_pk_mul_f32 v[4:5], v[10:11], v[4:5]
	v_and_b32_e32 v11, 0xffff0000, v92
	v_mul_f32_e32 v3, 0xbfb8aa3b, v6
	v_exp_f32_e32 v7, v3
	v_mul_f32_e32 v3, 0xbfb8aa3b, v11
	v_exp_f32_e32 v10, v3
	v_pk_mul_f32 v[4:5], v[12:13], v[4:5]
	v_mov_b32_e32 v28, v255
	v_cvt_pk_bf16_f32 v3, v4, v5
	v_add_f32_e32 v4, 1.0, v7
	v_add_f32_e32 v5, 1.0, v10
	v_rcp_f32_e32 v4, v4
	v_rcp_f32_e32 v5, v5
	v_and_b32_e32 v7, 0xffff0000, v8
	v_lshlrev_b32_e32 v10, 16, v8
	v_pk_mul_f32 v[6:7], v[10:11], v[6:7]
	v_and_b32_e32 v11, 0xffff0000, v93
	v_pk_mul_f32 v[4:5], v[4:5], v[6:7]
	v_lshlrev_b32_e32 v6, 16, v93
	v_mul_f32_e32 v7, 0xbfb8aa3b, v6
	v_exp_f32_e32 v7, v7
	v_mul_f32_e32 v8, 0xbfb8aa3b, v11
	v_exp_f32_e32 v8, v8
	v_cvt_pk_bf16_f32 v4, v4, v5
	v_add_f32_e32 v5, 1.0, v7
	v_rcp_f32_e32 v12, v5
	v_add_f32_e32 v5, 1.0, v8
	v_rcp_f32_e32 v13, v5
	v_and_b32_e32 v7, 0xffff0000, v9
	v_lshlrev_b32_e32 v10, 16, v9
	v_pk_mul_f32 v[6:7], v[10:11], v[6:7]
	s_waitcnt vmcnt(6)
	v_lshlrev_b32_e32 v10, 16, v86
	v_pk_mul_f32 v[6:7], v[12:13], v[6:7]
	v_and_b32_e32 v13, 0xffff0000, v86
	v_cvt_pk_bf16_f32 v5, v6, v7
	v_lshlrev_b64 v[6:7], 12, v[132:133]
	v_lshl_add_u64 v[6:7], s[0:1], 0, v[6:7]
	v_lshl_add_u64 v[6:7], v[6:7], 0, v[134:135]
	global_store_dwordx4 v[6:7], v[2:5], off
	s_lshl_b32 s27, s50, 8
	s_or_b32 s5, s22, s27
	v_mul_lo_u32 v2, v136, s45
	v_lshlrev_b32_e32 v3, 4, v143
	v_add3_u32 v2, s4, v2, v3
	v_mul_f32_e32 v3, 0xbfb8aa3b, v10
	v_exp_f32_e32 v6, v3
	v_mul_f32_e32 v3, 0xbfb8aa3b, v13
	v_exp_f32_e32 v7, v3
	ds_read_b128 v[2:5], v2
	v_add_f32_e32 v6, 1.0, v6
	v_rcp_f32_e32 v14, v6
	v_add_f32_e32 v6, 1.0, v7
	v_rcp_f32_e32 v15, v6
	v_mul_lo_u32 v6, v130, s45
	v_lshlrev_b32_e32 v7, 4, v137
	v_add3_u32 v6, s4, v6, v7
	ds_read_b128 v[6:9], v6
	s_waitcnt lgkmcnt(1)
	v_and_b32_e32 v11, 0xffff0000, v2
	v_lshlrev_b32_e32 v12, 16, v2
	v_pk_mul_f32 v[10:11], v[12:13], v[10:11]
	v_lshlrev_b32_e32 v12, 16, v87
	v_pk_mul_f32 v[10:11], v[14:15], v[10:11]
	v_and_b32_e32 v15, 0xffff0000, v87
	v_mul_f32_e32 v2, 0xbfb8aa3b, v12
	v_exp_f32_e32 v13, v2
	v_mul_f32_e32 v2, 0xbfb8aa3b, v15
	v_exp_f32_e32 v14, v2
	v_cvt_pk_bf16_f32 v2, v10, v11
	v_add_f32_e32 v10, 1.0, v13
	v_rcp_f32_e32 v10, v10
	v_add_f32_e32 v11, 1.0, v14
	v_rcp_f32_e32 v11, v11
	v_and_b32_e32 v13, 0xffff0000, v3
	v_lshlrev_b32_e32 v14, 16, v3
	v_pk_mul_f32 v[12:13], v[14:15], v[12:13]
	v_and_b32_e32 v15, 0xffff0000, v88
	v_pk_mul_f32 v[10:11], v[10:11], v[12:13]
	v_lshlrev_b32_e32 v12, 16, v88
	v_mul_f32_e32 v3, 0xbfb8aa3b, v12
	v_exp_f32_e32 v13, v3
	v_mul_f32_e32 v3, 0xbfb8aa3b, v15
	v_exp_f32_e32 v14, v3
	v_cvt_pk_bf16_f32 v3, v10, v11
	v_add_f32_e32 v10, 1.0, v13
	v_rcp_f32_e32 v10, v10
	v_add_f32_e32 v11, 1.0, v14
	v_rcp_f32_e32 v11, v11
	v_and_b32_e32 v13, 0xffff0000, v4
	v_lshlrev_b32_e32 v14, 16, v4
	v_pk_mul_f32 v[12:13], v[14:15], v[12:13]
	v_and_b32_e32 v15, 0xffff0000, v89
	v_pk_mul_f32 v[10:11], v[10:11], v[12:13]
	v_lshlrev_b32_e32 v12, 16, v89
	v_mul_f32_e32 v4, 0xbfb8aa3b, v12
	v_exp_f32_e32 v13, v4
	v_mul_f32_e32 v4, 0xbfb8aa3b, v15
	v_exp_f32_e32 v14, v4
	v_cvt_pk_bf16_f32 v4, v10, v11
	v_add_f32_e32 v10, 1.0, v13
	v_rcp_f32_e32 v10, v10
	v_add_f32_e32 v11, 1.0, v14
	v_rcp_f32_e32 v11, v11
	v_and_b32_e32 v13, 0xffff0000, v5
	v_lshlrev_b32_e32 v14, 16, v5
	v_pk_mul_f32 v[12:13], v[14:15], v[12:13]
	s_waitcnt vmcnt(6)
	v_and_b32_e32 v15, 0xffff0000, v82
	v_pk_mul_f32 v[10:11], v[10:11], v[12:13]
	v_lshlrev_b32_e32 v12, 16, v82
	v_mul_f32_e32 v13, 0xbfb8aa3b, v12
	v_mul_f32_e32 v14, 0xbfb8aa3b, v15
	v_exp_f32_e32 v13, v13
	v_exp_f32_e32 v14, v14
	v_cvt_pk_bf16_f32 v5, v10, v11
	v_lshlrev_b64 v[10:11], 12, v[126:127]
	v_lshl_add_u64 v[10:11], s[0:1], 0, v[10:11]
	v_lshl_add_u64 v[10:11], v[10:11], 0, v[128:129]
	global_store_dwordx4 v[10:11], v[2:5], off
	v_and_b32_e32 v11, 0xffff0000, v83
	s_waitcnt lgkmcnt(0)
	v_lshlrev_b32_e32 v10, 16, v7
	v_add_f32_e32 v2, 1.0, v13
	v_add_f32_e32 v3, 1.0, v14
	v_rcp_f32_e32 v2, v2
	v_rcp_f32_e32 v3, v3
	v_and_b32_e32 v13, 0xffff0000, v6
	v_lshlrev_b32_e32 v14, 16, v6
	v_pk_mul_f32 v[4:5], v[14:15], v[12:13]
	v_mul_f32_e32 v6, 0xbfb8aa3b, v11
	v_pk_mul_f32 v[2:3], v[2:3], v[4:5]
	v_lshlrev_b32_e32 v4, 16, v83
	v_mul_f32_e32 v5, 0xbfb8aa3b, v4
	v_exp_f32_e32 v5, v5
	v_exp_f32_e32 v6, v6
	v_cvt_pk_bf16_f32 v2, v2, v3
	s_lshl_b32 s33, s50, 2
	v_add_f32_e32 v3, 1.0, v5
	v_rcp_f32_e32 v12, v3
	v_add_f32_e32 v3, 1.0, v6
	v_and_b32_e32 v5, 0xffff0000, v7
	v_lshlrev_b32_e32 v6, 16, v84
	v_rcp_f32_e32 v13, v3
	v_pk_mul_f32 v[4:5], v[10:11], v[4:5]
	v_and_b32_e32 v11, 0xffff0000, v84
	v_mul_f32_e32 v3, 0xbfb8aa3b, v6
	v_exp_f32_e32 v7, v3
	v_mul_f32_e32 v3, 0xbfb8aa3b, v11
	v_exp_f32_e32 v10, v3
	v_pk_mul_f32 v[4:5], v[12:13], v[4:5]
	s_mov_b32 s24, 0
	v_cvt_pk_bf16_f32 v3, v4, v5
	v_add_f32_e32 v4, 1.0, v7
	v_add_f32_e32 v5, 1.0, v10
	v_rcp_f32_e32 v4, v4
	v_rcp_f32_e32 v5, v5
	v_and_b32_e32 v7, 0xffff0000, v8
	v_lshlrev_b32_e32 v10, 16, v8
	v_pk_mul_f32 v[6:7], v[10:11], v[6:7]
	v_and_b32_e32 v11, 0xffff0000, v85
	v_pk_mul_f32 v[4:5], v[4:5], v[6:7]
	v_lshlrev_b32_e32 v6, 16, v85
	v_mul_f32_e32 v7, 0xbfb8aa3b, v6
	v_exp_f32_e32 v7, v7
	v_mul_f32_e32 v8, 0xbfb8aa3b, v11
	v_exp_f32_e32 v8, v8
	v_cvt_pk_bf16_f32 v4, v4, v5
	v_add_f32_e32 v5, 1.0, v7
	v_rcp_f32_e32 v12, v5
	v_add_f32_e32 v5, 1.0, v8
	v_rcp_f32_e32 v13, v5
	v_and_b32_e32 v7, 0xffff0000, v9
	v_lshlrev_b32_e32 v10, 16, v9
	v_pk_mul_f32 v[6:7], v[10:11], v[6:7]
	s_waitcnt vmcnt(6)
	v_lshlrev_b32_e32 v10, 16, v78
	v_pk_mul_f32 v[6:7], v[12:13], v[6:7]
	v_and_b32_e32 v13, 0xffff0000, v78
	v_cvt_pk_bf16_f32 v5, v6, v7
	v_lshlrev_b64 v[6:7], 12, v[120:121]
	v_lshl_add_u64 v[6:7], s[0:1], 0, v[6:7]
	v_lshl_add_u64 v[6:7], v[6:7], 0, v[122:123]
	global_store_dwordx4 v[6:7], v[2:5], off
	s_mov_b32 s25, 2
	s_mov_b32 s26, 63
	v_mul_lo_u32 v2, v124, s45
	v_lshlrev_b32_e32 v3, 4, v131
	v_add3_u32 v2, s4, v2, v3
	v_mul_f32_e32 v3, 0xbfb8aa3b, v10
	v_exp_f32_e32 v6, v3
	v_mul_f32_e32 v3, 0xbfb8aa3b, v13
	v_exp_f32_e32 v7, v3
	ds_read_b128 v[2:5], v2
	v_add_f32_e32 v6, 1.0, v6
	v_rcp_f32_e32 v14, v6
	v_add_f32_e32 v6, 1.0, v7
	v_rcp_f32_e32 v15, v6
	v_mul_lo_u32 v6, v118, s45
	v_lshlrev_b32_e32 v7, 4, v125
	v_add3_u32 v6, s4, v6, v7
	ds_read_b128 v[6:9], v6
	s_waitcnt lgkmcnt(1)
	v_and_b32_e32 v11, 0xffff0000, v2
	v_lshlrev_b32_e32 v12, 16, v2
	v_pk_mul_f32 v[10:11], v[12:13], v[10:11]
	v_lshlrev_b32_e32 v12, 16, v79
	v_pk_mul_f32 v[10:11], v[14:15], v[10:11]
	v_and_b32_e32 v15, 0xffff0000, v79
	v_mul_f32_e32 v2, 0xbfb8aa3b, v12
	v_exp_f32_e32 v13, v2
	v_mul_f32_e32 v2, 0xbfb8aa3b, v15
	v_exp_f32_e32 v14, v2
	v_cvt_pk_bf16_f32 v2, v10, v11
	v_add_f32_e32 v10, 1.0, v13
	v_rcp_f32_e32 v10, v10
	v_add_f32_e32 v11, 1.0, v14
	v_rcp_f32_e32 v11, v11
	v_and_b32_e32 v13, 0xffff0000, v3
	v_lshlrev_b32_e32 v14, 16, v3
	v_pk_mul_f32 v[12:13], v[14:15], v[12:13]
	v_and_b32_e32 v15, 0xffff0000, v80
	v_pk_mul_f32 v[10:11], v[10:11], v[12:13]
	v_lshlrev_b32_e32 v12, 16, v80
	v_mul_f32_e32 v3, 0xbfb8aa3b, v12
	v_exp_f32_e32 v13, v3
	v_mul_f32_e32 v3, 0xbfb8aa3b, v15
	v_exp_f32_e32 v14, v3
	v_cvt_pk_bf16_f32 v3, v10, v11
	v_add_f32_e32 v10, 1.0, v13
	v_rcp_f32_e32 v10, v10
	v_add_f32_e32 v11, 1.0, v14
	v_rcp_f32_e32 v11, v11
	v_and_b32_e32 v13, 0xffff0000, v4
	v_lshlrev_b32_e32 v14, 16, v4
	v_pk_mul_f32 v[12:13], v[14:15], v[12:13]
	v_and_b32_e32 v15, 0xffff0000, v81
	v_pk_mul_f32 v[10:11], v[10:11], v[12:13]
	v_lshlrev_b32_e32 v12, 16, v81
	v_mul_f32_e32 v4, 0xbfb8aa3b, v12
	v_exp_f32_e32 v13, v4
	v_mul_f32_e32 v4, 0xbfb8aa3b, v15
	v_exp_f32_e32 v14, v4
	v_cvt_pk_bf16_f32 v4, v10, v11
	v_add_f32_e32 v10, 1.0, v13
	v_rcp_f32_e32 v10, v10
	v_add_f32_e32 v11, 1.0, v14
	v_rcp_f32_e32 v11, v11
	v_and_b32_e32 v13, 0xffff0000, v5
	v_lshlrev_b32_e32 v14, 16, v5
	v_pk_mul_f32 v[12:13], v[14:15], v[12:13]
	s_waitcnt vmcnt(6)
	v_and_b32_e32 v15, 0xffff0000, v74
	v_pk_mul_f32 v[10:11], v[10:11], v[12:13]
	v_lshlrev_b32_e32 v12, 16, v74
	v_mul_f32_e32 v13, 0xbfb8aa3b, v12
	v_mul_f32_e32 v14, 0xbfb8aa3b, v15
	v_exp_f32_e32 v13, v13
	v_exp_f32_e32 v14, v14
	v_cvt_pk_bf16_f32 v5, v10, v11
	v_lshlrev_b64 v[10:11], 12, v[114:115]
	v_lshl_add_u64 v[10:11], s[0:1], 0, v[10:11]
	v_lshl_add_u64 v[10:11], v[10:11], 0, v[116:117]
	global_store_dwordx4 v[10:11], v[2:5], off
	v_and_b32_e32 v11, 0xffff0000, v75
	s_waitcnt lgkmcnt(0)
	v_lshlrev_b32_e32 v10, 16, v7
	v_add_f32_e32 v2, 1.0, v13
	v_add_f32_e32 v3, 1.0, v14
	v_rcp_f32_e32 v2, v2
	v_rcp_f32_e32 v3, v3
	v_and_b32_e32 v13, 0xffff0000, v6
	v_lshlrev_b32_e32 v14, 16, v6
	v_pk_mul_f32 v[4:5], v[14:15], v[12:13]
	v_mul_f32_e32 v6, 0xbfb8aa3b, v11
	v_pk_mul_f32 v[2:3], v[2:3], v[4:5]
	v_lshlrev_b32_e32 v4, 16, v75
	v_mul_f32_e32 v5, 0xbfb8aa3b, v4
	v_exp_f32_e32 v5, v5
	v_exp_f32_e32 v6, v6
	v_cvt_pk_bf16_f32 v2, v2, v3
	v_mov_b32_e32 v196, 0
	v_add_f32_e32 v3, 1.0, v5
	v_rcp_f32_e32 v12, v3
	v_add_f32_e32 v3, 1.0, v6
	v_and_b32_e32 v5, 0xffff0000, v7
	v_lshlrev_b32_e32 v6, 16, v76
	v_rcp_f32_e32 v13, v3
	v_pk_mul_f32 v[4:5], v[10:11], v[4:5]
	v_and_b32_e32 v11, 0xffff0000, v76
	v_mul_f32_e32 v3, 0xbfb8aa3b, v6
	v_exp_f32_e32 v7, v3
	v_mul_f32_e32 v3, 0xbfb8aa3b, v11
	v_exp_f32_e32 v10, v3
	v_pk_mul_f32 v[4:5], v[12:13], v[4:5]
	v_mov_b32_e32 v197, 0xf149f2ca
	v_cvt_pk_bf16_f32 v3, v4, v5
	v_add_f32_e32 v4, 1.0, v7
	v_add_f32_e32 v5, 1.0, v10
	v_rcp_f32_e32 v4, v4
	v_rcp_f32_e32 v5, v5
	v_and_b32_e32 v7, 0xffff0000, v8
	v_lshlrev_b32_e32 v10, 16, v8
	v_pk_mul_f32 v[6:7], v[10:11], v[6:7]
	v_and_b32_e32 v11, 0xffff0000, v77
	v_pk_mul_f32 v[4:5], v[4:5], v[6:7]
	v_lshlrev_b32_e32 v6, 16, v77
	v_mul_f32_e32 v7, 0xbfb8aa3b, v6
	v_exp_f32_e32 v7, v7
	v_mul_f32_e32 v8, 0xbfb8aa3b, v11
	v_exp_f32_e32 v8, v8
	v_cvt_pk_bf16_f32 v4, v4, v5
	v_add_f32_e32 v5, 1.0, v7
	v_rcp_f32_e32 v12, v5
	v_add_f32_e32 v5, 1.0, v8
	v_rcp_f32_e32 v13, v5
	v_and_b32_e32 v7, 0xffff0000, v9
	v_lshlrev_b32_e32 v10, 16, v9
	v_pk_mul_f32 v[6:7], v[10:11], v[6:7]
	s_waitcnt vmcnt(6)
	v_lshlrev_b32_e32 v10, 16, v70
	v_pk_mul_f32 v[6:7], v[12:13], v[6:7]
	v_and_b32_e32 v13, 0xffff0000, v70
	v_cvt_pk_bf16_f32 v5, v6, v7
	v_lshlrev_b64 v[6:7], 12, v[108:109]
	v_lshl_add_u64 v[6:7], s[0:1], 0, v[6:7]
	v_lshl_add_u64 v[6:7], v[6:7], 0, v[110:111]
	global_store_dwordx4 v[6:7], v[2:5], off
	s_nop 1
	v_mul_lo_u32 v2, v112, s45
	v_lshlrev_b32_e32 v3, 4, v119
	v_add3_u32 v2, s4, v2, v3
	v_mul_f32_e32 v3, 0xbfb8aa3b, v10
	v_exp_f32_e32 v6, v3
	v_mul_f32_e32 v3, 0xbfb8aa3b, v13
	v_exp_f32_e32 v7, v3
	ds_read_b128 v[2:5], v2
	v_add_f32_e32 v6, 1.0, v6
	v_rcp_f32_e32 v14, v6
	v_add_f32_e32 v6, 1.0, v7
	v_rcp_f32_e32 v15, v6
	v_mul_lo_u32 v6, v106, s45
	v_add3_u32 v0, s4, v6, v0
	ds_read_b128 v[6:9], v0
	s_waitcnt lgkmcnt(1)
	v_and_b32_e32 v11, 0xffff0000, v2
	v_lshlrev_b32_e32 v12, 16, v2
	v_pk_mul_f32 v[10:11], v[12:13], v[10:11]
	v_lshlrev_b32_e32 v12, 16, v71
	v_pk_mul_f32 v[10:11], v[14:15], v[10:11]
	v_and_b32_e32 v15, 0xffff0000, v71
	v_mul_f32_e32 v0, 0xbfb8aa3b, v12
	v_exp_f32_e32 v0, v0
	v_mul_f32_e32 v2, 0xbfb8aa3b, v15
	v_exp_f32_e32 v13, v2
	v_cvt_pk_bf16_f32 v2, v10, v11
	v_add_f32_e32 v0, 1.0, v0
	v_rcp_f32_e32 v10, v0
	v_add_f32_e32 v0, 1.0, v13
	v_rcp_f32_e32 v11, v0
	v_and_b32_e32 v13, 0xffff0000, v3
	v_lshlrev_b32_e32 v14, 16, v3
	v_pk_mul_f32 v[12:13], v[14:15], v[12:13]
	v_and_b32_e32 v15, 0xffff0000, v72
	v_pk_mul_f32 v[10:11], v[10:11], v[12:13]
	v_lshlrev_b32_e32 v12, 16, v72
	v_mul_f32_e32 v0, 0xbfb8aa3b, v12
	v_exp_f32_e32 v0, v0
	v_mul_f32_e32 v3, 0xbfb8aa3b, v15
	v_exp_f32_e32 v13, v3
	v_cvt_pk_bf16_f32 v3, v10, v11
	v_add_f32_e32 v0, 1.0, v0
	v_rcp_f32_e32 v10, v0
	v_add_f32_e32 v0, 1.0, v13
	v_rcp_f32_e32 v11, v0
	v_and_b32_e32 v13, 0xffff0000, v4
	v_lshlrev_b32_e32 v14, 16, v4
	v_pk_mul_f32 v[12:13], v[14:15], v[12:13]
	v_and_b32_e32 v15, 0xffff0000, v73
	v_pk_mul_f32 v[10:11], v[10:11], v[12:13]
	v_lshlrev_b32_e32 v12, 16, v73
	v_mul_f32_e32 v0, 0xbfb8aa3b, v12
	v_exp_f32_e32 v0, v0
	v_mul_f32_e32 v4, 0xbfb8aa3b, v15
	v_exp_f32_e32 v13, v4
	v_cvt_pk_bf16_f32 v4, v10, v11
	v_add_f32_e32 v0, 1.0, v0
	v_rcp_f32_e32 v10, v0
	v_add_f32_e32 v0, 1.0, v13
	v_rcp_f32_e32 v11, v0
	v_and_b32_e32 v13, 0xffff0000, v5
	v_lshlrev_b32_e32 v14, 16, v5
	v_pk_mul_f32 v[12:13], v[14:15], v[12:13]
	s_waitcnt vmcnt(6)
	v_and_b32_e32 v15, 0xffff0000, v66
	v_pk_mul_f32 v[10:11], v[10:11], v[12:13]
	v_lshlrev_b32_e32 v12, 16, v66
	v_mul_f32_e32 v0, 0xbfb8aa3b, v12
	v_exp_f32_e32 v0, v0
	v_mul_f32_e32 v13, 0xbfb8aa3b, v15
	v_exp_f32_e32 v13, v13
	v_cvt_pk_bf16_f32 v5, v10, v11
	v_lshlrev_b64 v[10:11], 12, v[102:103]
	v_lshl_add_u64 v[10:11], s[0:1], 0, v[10:11]
	v_lshl_add_u64 v[10:11], v[10:11], 0, v[104:105]
	v_add_f32_e32 v0, 1.0, v0
	global_store_dwordx4 v[10:11], v[2:5], off
	s_waitcnt lgkmcnt(0)
	v_lshlrev_b32_e32 v14, 16, v6
	v_and_b32_e32 v11, 0xffff0000, v67
	v_rcp_f32_e32 v2, v0
	v_add_f32_e32 v0, 1.0, v13
	v_rcp_f32_e32 v3, v0
	v_and_b32_e32 v13, 0xffff0000, v6
	v_pk_mul_f32 v[4:5], v[14:15], v[12:13]
	v_lshlrev_b32_e32 v10, 16, v7
	v_pk_mul_f32 v[2:3], v[2:3], v[4:5]
	v_lshlrev_b32_e32 v4, 16, v67
	v_mul_f32_e32 v0, 0xbfb8aa3b, v4
	v_exp_f32_e32 v0, v0
	v_mul_f32_e32 v5, 0xbfb8aa3b, v11
	v_exp_f32_e32 v5, v5
	v_lshlrev_b32_e32 v6, 16, v68
	v_add_f32_e32 v0, 1.0, v0
	v_rcp_f32_e32 v12, v0
	v_add_f32_e32 v0, 1.0, v5
	v_and_b32_e32 v5, 0xffff0000, v7
	v_rcp_f32_e32 v13, v0
	v_pk_mul_f32 v[4:5], v[10:11], v[4:5]
	v_and_b32_e32 v11, 0xffff0000, v68
	v_mul_f32_e32 v0, 0xbfb8aa3b, v6
	v_cvt_pk_bf16_f32 v2, v2, v3
	v_exp_f32_e32 v0, v0
	v_mul_f32_e32 v3, 0xbfb8aa3b, v11
	v_exp_f32_e32 v7, v3
	v_pk_mul_f32 v[4:5], v[12:13], v[4:5]
	v_add_f32_e32 v0, 1.0, v0
	v_cvt_pk_bf16_f32 v3, v4, v5
	v_rcp_f32_e32 v4, v0
	v_add_f32_e32 v0, 1.0, v7
	v_rcp_f32_e32 v5, v0
	v_and_b32_e32 v7, 0xffff0000, v8
	v_lshlrev_b32_e32 v10, 16, v8
	v_pk_mul_f32 v[6:7], v[10:11], v[6:7]
	v_and_b32_e32 v11, 0xffff0000, v69
	v_pk_mul_f32 v[4:5], v[4:5], v[6:7]
	v_lshlrev_b32_e32 v6, 16, v69
	v_mul_f32_e32 v0, 0xbfb8aa3b, v6
	v_exp_f32_e32 v0, v0
	v_mul_f32_e32 v7, 0xbfb8aa3b, v11
	v_exp_f32_e32 v7, v7
	v_lshlrev_b32_e32 v10, 16, v9
	v_add_f32_e32 v0, 1.0, v0
	v_rcp_f32_e32 v12, v0
	v_add_f32_e32 v0, 1.0, v7
	v_rcp_f32_e32 v13, v0
	v_and_b32_e32 v7, 0xffff0000, v9
	v_pk_mul_f32 v[6:7], v[10:11], v[6:7]
	v_cvt_pk_bf16_f32 v4, v4, v5
	v_pk_mul_f32 v[6:7], v[12:13], v[6:7]
	s_nop 0
	v_cvt_pk_bf16_f32 v5, v6, v7
	v_lshlrev_b64 v[6:7], 12, v[98:99]
	v_lshl_add_u64 v[6:7], s[0:1], 0, v[6:7]
	v_lshl_add_u64 v[6:7], v[6:7], 0, v[100:101]
	global_store_dwordx4 v[6:7], v[2:5], off
	s_barrier
	s_branch .Lq_read
